# grid barrier fan-out: last arriver bumps all 8 per-XCD release words itself; mates poll per-XCD word (with XCD-balanced FFN-up)
# speedup vs baseline: 1.0069x; 1.0029x over previous
.LBB0_66:
	s_or_b64 exec, exec, s[10:11]
	s_and_saveexec_b64 s[4:5], s[12:13]
	s_cbranch_execz .LBB0_68
	v_mov_b32_e32 v2, 1
	global_atomic_add v[0:1], v2, off
	v_mov_b32_e32 v3, 0xfc02400
	global_atomic_add v3, v2, s[88:89] offset:0
	global_atomic_add v3, v2, s[88:89] offset:256
	global_atomic_add v3, v2, s[88:89] offset:512
	global_atomic_add v3, v2, s[88:89] offset:768
	global_atomic_add v3, v2, s[88:89] offset:1024
	global_atomic_add v3, v2, s[88:89] offset:1280
	global_atomic_add v3, v2, s[88:89] offset:1536
	global_atomic_add v3, v2, s[88:89] offset:1792

.LBB0_181:
	s_or_b64 exec, exec, s[12:13]
	s_and_saveexec_b64 s[6:7], s[14:15]
	s_cbranch_execz .LBB0_183
	v_mov_b32_e32 v2, 1
	global_atomic_add v[0:1], v2, off
	v_mov_b32_e32 v3, 0xfc02400
	global_atomic_add v3, v2, s[88:89] offset:0
	global_atomic_add v3, v2, s[88:89] offset:256
	global_atomic_add v3, v2, s[88:89] offset:512
	global_atomic_add v3, v2, s[88:89] offset:768
	global_atomic_add v3, v2, s[88:89] offset:1024
	global_atomic_add v3, v2, s[88:89] offset:1280
	global_atomic_add v3, v2, s[88:89] offset:1536
	global_atomic_add v3, v2, s[88:89] offset:1792

.LBB0_244:
	s_or_b64 exec, exec, s[12:13]
	s_and_saveexec_b64 s[4:5], s[14:15]
	s_cbranch_execz .LBB0_246
	v_mov_b32_e32 v2, 1
	global_atomic_add v[0:1], v2, off
	v_mov_b32_e32 v3, 0xfc02400
	global_atomic_add v3, v2, s[88:89] offset:0
	global_atomic_add v3, v2, s[88:89] offset:256
	global_atomic_add v3, v2, s[88:89] offset:512
	global_atomic_add v3, v2, s[88:89] offset:768
	global_atomic_add v3, v2, s[88:89] offset:1024
	global_atomic_add v3, v2, s[88:89] offset:1280
	global_atomic_add v3, v2, s[88:89] offset:1536
	global_atomic_add v3, v2, s[88:89] offset:1792

.LBB0_397:
	s_or_b64 exec, exec, s[6:7]
	s_and_saveexec_b64 s[4:5], s[10:11]
	s_cbranch_execz .LBB0_399
	v_mov_b32_e32 v2, 1
	global_atomic_add v[0:1], v2, off
	v_mov_b32_e32 v3, 0xfc02400
	global_atomic_add v3, v2, s[88:89] offset:0
	global_atomic_add v3, v2, s[88:89] offset:256
	global_atomic_add v3, v2, s[88:89] offset:512
	global_atomic_add v3, v2, s[88:89] offset:768
	global_atomic_add v3, v2, s[88:89] offset:1024
	global_atomic_add v3, v2, s[88:89] offset:1280
	global_atomic_add v3, v2, s[88:89] offset:1536
	global_atomic_add v3, v2, s[88:89] offset:1792

.LBB0_1229:
	s_or_b64 exec, exec, s[8:9]
	s_and_saveexec_b64 s[2:3], s[10:11]
	s_cbranch_execz .LBB0_1231
	v_mov_b32_e32 v2, 1
	global_atomic_add v[0:1], v2, off
	v_mov_b32_e32 v3, 0xfc02400
	global_atomic_add v3, v2, s[88:89] offset:0
	global_atomic_add v3, v2, s[88:89] offset:256
	global_atomic_add v3, v2, s[88:89] offset:512
	global_atomic_add v3, v2, s[88:89] offset:768
	global_atomic_add v3, v2, s[88:89] offset:1024
	global_atomic_add v3, v2, s[88:89] offset:1280
	global_atomic_add v3, v2, s[88:89] offset:1536
	global_atomic_add v3, v2, s[88:89] offset:1792

.LBB0_1623:
	s_or_b64 exec, exec, s[2:3]
	s_and_saveexec_b64 s[2:3], s[4:5]
	s_cbranch_execz .LBB0_1625
	v_mov_b32_e32 v2, 1
	global_atomic_add v[0:1], v2, off
	v_mov_b32_e32 v3, 0xfc02400
	global_atomic_add v3, v2, s[88:89] offset:0
	global_atomic_add v3, v2, s[88:89] offset:256
	global_atomic_add v3, v2, s[88:89] offset:512
	global_atomic_add v3, v2, s[88:89] offset:768
	global_atomic_add v3, v2, s[88:89] offset:1024
	global_atomic_add v3, v2, s[88:89] offset:1280
	global_atomic_add v3, v2, s[88:89] offset:1536
	global_atomic_add v3, v2, s[88:89] offset:1792
